# P1 row sums: shfl_xor butterfly via DPP / permlane swaps instead of six ds_bpermute round trips per row
# baseline (speedup 1.0000x reference)
.LBB0_184:
	s_or_b64 exec, exec, s[4:5]
	s_lshl_b32 s0, s3, 6
	s_lshl_b32 s1, s62, 3
	s_add_i32 s6, s0, s1
	s_ashr_i32 s0, s6, 8
	s_ashr_i32 s1, s0, 31
	s_lshl_b64 s[0:1], s[0:1], 19
	s_add_u32 s5, s52, s0
	s_addc_u32 s4, s53, s1
	s_ashr_i32 s7, s6, 31
	s_lshl_b64 s[0:1], s[6:7], 12
	s_add_u32 s0, s36, s0
	v_ashrrev_i32_e32 v21, 31, v20
	s_addc_u32 s1, s37, s1
	v_lshlrev_b64 v[88:89], 4, v[20:21]
	v_lshl_add_u64 v[0:1], s[0:1], 0, v[88:89]
	s_waitcnt lgkmcnt(0)
	s_barrier
	global_load_dwordx4 v[8:11], v[0:1], off nt
	global_load_dwordx4 v[16:19], v[0:1], off offset:1024 nt
	global_load_dwordx4 v[32:35], v[0:1], off offset:3072 nt
	global_load_dwordx4 v[24:27], v[0:1], off offset:2048 nt
	v_mbcnt_lo_u32_b32 v0, -1, 0
	s_or_b32 s0, s6, 1
	v_mbcnt_hi_u32_b32 v2, -1, v0
	s_ashr_i32 s1, s0, 31
	v_and_b32_e32 v0, 64, v2
	s_lshl_b64 s[0:1], s[0:1], 12
	v_xor_b32_e32 v1, 1, v2
	v_add_u32_e32 v12, 64, v0
	s_add_u32 s0, s36, s0
	v_cmp_lt_i32_e32 vcc, v1, v12
	s_addc_u32 s1, s37, s1
	v_xor_b32_e32 v3, 2, v2
	v_cndmask_b32_e32 v13, v2, v1, vcc
	v_lshl_add_u64 v[0:1], s[0:1], 0, v[88:89]
	global_load_dwordx4 v[52:55], v[0:1], off nt
	global_load_dwordx4 v[40:43], v[0:1], off offset:1024 nt
	global_load_dwordx4 v[48:51], v[0:1], off offset:2048 nt
	global_load_dwordx4 v[36:39], v[0:1], off offset:3072 nt
	v_xor_b32_e32 v4, 4, v2
	v_cmp_lt_i32_e32 vcc, v3, v12
	v_xor_b32_e32 v5, 8, v2
	v_xor_b32_e32 v6, 16, v2
	v_cndmask_b32_e32 v3, v2, v3, vcc
	v_cmp_lt_i32_e32 vcc, v4, v12
	v_xor_b32_e32 v7, 32, v2
	v_lshlrev_b32_e32 v109, 2, v3
	v_cndmask_b32_e32 v4, v2, v4, vcc
	v_cmp_lt_i32_e32 vcc, v5, v12
	v_lshlrev_b32_e32 v108, 2, v4
	v_lshlrev_b32_e32 v110, 2, v13
	v_cndmask_b32_e32 v5, v2, v5, vcc
	v_cmp_lt_i32_e32 vcc, v6, v12
	v_lshlrev_b32_e32 v107, 2, v5
	s_or_b32 s0, s6, 2
	v_cndmask_b32_e32 v6, v2, v6, vcc
	v_cmp_lt_i32_e32 vcc, v7, v12
	v_lshlrev_b32_e32 v106, 2, v6
	s_ashr_i32 s1, s0, 31
	v_cndmask_b32_e32 v2, v2, v7, vcc
	v_lshlrev_b32_e32 v105, 2, v2
	s_lshl_b64 s[0:1], s[0:1], 12
	s_add_u32 s0, s36, s0
	s_addc_u32 s1, s37, s1
	v_mov_b32_e32 v104, 0x358637bd
	s_mov_b32 s3, 0xf800000
	s_or_b32 s8, s6, 3
	s_ashr_i32 s9, s8, 31
	v_mov_b32_e32 v111, 0x260
	v_lshl_add_u32 v30, v20, 4, 0
	v_lshlrev_b32_e32 v85, 8, v20
	v_and_b32_e32 v84, 15, v20
	s_waitcnt vmcnt(7)
	v_pk_mul_f32 v[0:1], v[10:11], v[10:11]
	v_pk_mul_f32 v[2:3], v[8:9], v[8:9]
	s_waitcnt vmcnt(6)
	v_pk_mul_f32 v[4:5], v[18:19], v[18:19]
	v_pk_mul_f32 v[6:7], v[16:17], v[16:17]
	v_pk_mov_b32 v[22:23], v[2:3], v[0:1] op_sel:[1,0]
	v_mov_b32_e32 v3, v1
	v_pk_mov_b32 v[0:1], v[6:7], v[4:5] op_sel:[1,0]
	v_mov_b32_e32 v7, v5
	s_waitcnt vmcnt(5)
	v_mul_f32_e32 v15, v32, v32
	s_waitcnt vmcnt(4)
	v_mul_f32_e32 v12, v25, v25
	v_mul_f32_e32 v14, v27, v27
	v_pk_add_f32 v[2:3], v[22:23], v[2:3]
	v_pk_add_f32 v[0:1], v[0:1], v[6:7]
	v_mul_f32_e32 v21, v33, v33
	v_mul_f32_e32 v28, v34, v34
	v_mul_f32_e32 v29, v35, v35
	v_pk_fma_f32 v[4:5], v[24:25], v[24:25], v[12:13] op_sel_hi:[1,1,0]
	v_pk_fma_f32 v[12:13], v[26:27], v[26:27], v[14:15] op_sel_hi:[1,1,0]
	v_pk_add_f32 v[2:3], v[2:3], v[2:3] op_sel:[0,1] op_sel_hi:[1,0]
	v_pk_add_f32 v[0:1], v[0:1], v[0:1] op_sel:[0,1] op_sel_hi:[1,0]
	v_mov_b32_e32 v5, v28
	v_mov_b32_e32 v13, v29
	v_mov_b32_e32 v3, v15
	v_mov_b32_e32 v1, v21
	v_pk_add_f32 v[4:5], v[4:5], v[12:13]
	v_pk_add_f32 v[0:1], v[2:3], v[0:1]
	s_nop 0
	v_pk_add_f32 v[0:1], v[0:1], v[4:5]
	s_waitcnt vmcnt(3)
	v_pk_mul_f32 v[4:5], v[52:53], v[52:53]
	v_add_f32_e32 v2, v0, v1
	v_lshl_add_u64 v[0:1], s[0:1], 0, v[88:89]
	global_load_dwordx4 v[64:67], v[0:1], off nt
	global_load_dwordx4 v[60:63], v[0:1], off offset:1024 nt
	global_load_dwordx4 v[56:59], v[0:1], off offset:2048 nt
	global_load_dwordx4 v[44:47], v[0:1], off offset:3072 nt
	s_lshl_b64 s[0:1], s[8:9], 12
	s_waitcnt lgkmcnt(0)
	s_nop 1
	v_add_f32_dpp v2, v2, v2 quad_perm:[1,0,3,2] row_mask:0xf bank_mask:0xf
	s_add_u32 s0, s36, s0
	s_addc_u32 s1, s37, s1
	s_lshl_b32 s7, s6, 7
	v_lshl_add_u64 v[0:1], s[0:1], 0, v[88:89]
	s_waitcnt lgkmcnt(0)
	s_nop 1
	v_add_f32_dpp v2, v2, v2 quad_perm:[2,3,0,1] row_mask:0xf bank_mask:0xf
	s_and_b32 s7, s7, 0x7c00
	global_load_dwordx4 v[76:79], v[0:1], off nt
	global_load_dwordx4 v[68:71], v[0:1], off offset:1024 nt
	s_add_u32 s10, s5, s7
	s_addc_u32 s11, s4, 0
	s_waitcnt lgkmcnt(0)
	s_nop 1
	v_add_f32_dpp v2, v2, v2 row_half_mirror row_mask:0xf bank_mask:0xf
	s_or_b32 s0, s6, 4
	s_ashr_i32 s1, s0, 31
	s_lshl_b64 s[0:1], s[0:1], 12
	global_load_dwordx4 v[80:83], v[0:1], off offset:2048 nt
	global_load_dwordx4 v[72:75], v[0:1], off offset:3072 nt
	s_waitcnt lgkmcnt(0)
	s_nop 1
	v_add_f32_dpp v6, v2, v2 row_mirror row_mask:0xf bank_mask:0xf
	v_pk_mul_f32 v[2:3], v[54:55], v[54:55]
	s_add_u32 s8, s36, s0
	v_pk_mov_b32 v[12:13], v[4:5], v[2:3] op_sel:[1,0]
	v_mov_b32_e32 v5, v3
	s_waitcnt lgkmcnt(0)
	v_mov_b32_e32 v7, v6
	s_nop 1
	v_permlane16_swap_b32_e32 v7, v6
	v_add_f32_e32 v14, v6, v7
	v_pk_add_f32 v[2:3], v[12:13], v[4:5]
	s_waitcnt vmcnt(10)
	v_pk_mul_f32 v[6:7], v[42:43], v[42:43]
	v_pk_add_f32 v[2:3], v[2:3], v[2:3] op_sel:[0,1] op_sel_hi:[1,0]
	s_addc_u32 s9, s37, s1
	s_waitcnt lgkmcnt(0)
	v_mov_b32_e32 v15, v14
	s_nop 1
	v_permlane32_swap_b32_e32 v15, v14
	v_add_f32_e32 v4, v14, v15
	v_fmamk_f32 v4, v4, 0x3a800000, v104
	v_mul_f32_e32 v5, 0x4f800000, v4
	v_cmp_gt_f32_e32 vcc, s3, v4
	s_nop 1
	v_cndmask_b32_e32 v14, v4, v5, vcc
	v_pk_mul_f32 v[4:5], v[40:41], v[40:41]
	v_sqrt_f32_e32 v15, v14
	v_pk_mov_b32 v[12:13], v[4:5], v[6:7] op_sel:[1,0]
	v_mov_b32_e32 v5, v7
	v_pk_add_f32 v[4:5], v[12:13], v[4:5]
	s_waitcnt vmcnt(8)
	v_mul_f32_e32 v6, v36, v36
	v_mul_f32_e32 v7, v37, v37
	v_pk_add_f32 v[4:5], v[4:5], v[4:5] op_sel:[0,1] op_sel_hi:[1,0]
	v_mov_b32_e32 v3, v6
	v_mov_b32_e32 v5, v7
	v_pk_add_f32 v[2:3], v[2:3], v[4:5]
	v_mul_f32_e32 v4, v49, v49
	v_mul_f32_e32 v6, v51, v51
	v_mul_f32_e32 v12, v38, v38
	v_mul_f32_e32 v13, v39, v39
	v_pk_fma_f32 v[4:5], v[48:49], v[48:49], v[4:5] op_sel_hi:[1,1,0]
	v_pk_fma_f32 v[6:7], v[50:51], v[50:51], v[6:7] op_sel_hi:[1,1,0]
	v_mov_b32_e32 v5, v12
	v_mov_b32_e32 v7, v13
	v_pk_add_f32 v[4:5], v[4:5], v[6:7]
	s_nop 0
	v_pk_add_f32 v[2:3], v[2:3], v[4:5]
	v_add_u32_e32 v4, -1, v15
	v_add_f32_e32 v2, v2, v3
	v_fma_f32 v5, -v4, v15, v14
	v_cmp_ge_f32_e64 s[0:1], 0, v5
	v_add_u32_e32 v5, 1, v15
	v_fma_f32 v6, -v5, v15, v14
	s_waitcnt lgkmcnt(0)
	s_nop 1
	v_add_f32_dpp v2, v2, v2 quad_perm:[1,0,3,2] row_mask:0xf bank_mask:0xf
	v_cndmask_b32_e64 v4, v15, v4, s[0:1]
	v_cmp_lt_f32_e64 s[0:1], 0, v6
	s_waitcnt lgkmcnt(0)
	s_nop 1
	v_add_f32_dpp v2, v2, v2 quad_perm:[2,3,0,1] row_mask:0xf bank_mask:0xf
	v_cndmask_b32_e64 v4, v4, v5, s[0:1]
	v_mul_f32_e32 v5, 0x37800000, v4
	v_cndmask_b32_e32 v4, v4, v5, vcc
	v_cmp_class_f32_e32 vcc, v14, v111
	s_waitcnt lgkmcnt(0)
	s_nop 1
	v_add_f32_dpp v2, v2, v2 row_half_mirror row_mask:0xf bank_mask:0xf
	v_cndmask_b32_e32 v12, v4, v14, vcc
	v_div_scale_f32 v13, s[0:1], v12, v12, 1.0
	v_rcp_f32_e32 v14, v13
	s_waitcnt lgkmcnt(0)
	s_nop 1
	v_add_f32_dpp v2, v2, v2 row_mirror row_mask:0xf bank_mask:0xf
	v_div_scale_f32 v15, vcc, 1.0, v12, 1.0
	v_fma_f32 v0, -v13, v14, 1.0
	v_fmac_f32_e32 v14, v0, v14
	s_waitcnt lgkmcnt(0)
	v_mov_b32_e32 v3, v2
	s_nop 1
	v_permlane16_swap_b32_e32 v3, v2
	v_add_f32_e32 v0, v2, v3
	s_waitcnt vmcnt(7)
	v_pk_mul_f32 v[2:3], v[64:65], v[64:65]
	v_mul_f32_e32 v21, v15, v14
	v_fma_f32 v22, -v13, v21, v15
	v_fmac_f32_e32 v21, v22, v14
	s_waitcnt lgkmcnt(0)
	v_mov_b32_e32 v1, v0
	s_nop 1
	v_permlane32_swap_b32_e32 v1, v0
	v_add_f32_e32 v0, v0, v1
	v_fmamk_f32 v0, v0, 0x3a800000, v104
	v_mul_f32_e32 v1, 0x4f800000, v0
	v_cmp_gt_f32_e64 s[0:1], s3, v0
	s_nop 1
	v_cndmask_b32_e64 v23, v0, v1, s[0:1]
	v_pk_mul_f32 v[0:1], v[66:67], v[66:67]
	v_sqrt_f32_e32 v28, v23
	v_pk_mov_b32 v[4:5], v[2:3], v[0:1] op_sel:[1,0]
	v_mov_b32_e32 v3, v1
	v_pk_add_f32 v[0:1], v[4:5], v[2:3]
	s_waitcnt vmcnt(6)
	v_pk_mul_f32 v[2:3], v[62:63], v[62:63]
	v_pk_mul_f32 v[4:5], v[60:61], v[60:61]
	v_pk_add_f32 v[0:1], v[0:1], v[0:1] op_sel:[0,1] op_sel_hi:[1,0]
	v_pk_mov_b32 v[6:7], v[4:5], v[2:3] op_sel:[1,0]
	v_mov_b32_e32 v5, v3
	v_pk_add_f32 v[2:3], v[6:7], v[4:5]
	s_waitcnt vmcnt(4)
	v_mul_f32_e32 v4, v44, v44
	v_mul_f32_e32 v5, v45, v45
	v_pk_add_f32 v[2:3], v[2:3], v[2:3] op_sel:[0,1] op_sel_hi:[1,0]
	v_mov_b32_e32 v1, v4
	v_mov_b32_e32 v3, v5
	v_pk_add_f32 v[0:1], v[0:1], v[2:3]
	v_mul_f32_e32 v2, v57, v57
	v_mul_f32_e32 v4, v59, v59
	v_mul_f32_e32 v6, v46, v46
	v_mul_f32_e32 v7, v47, v47
	v_pk_fma_f32 v[2:3], v[56:57], v[56:57], v[2:3] op_sel_hi:[1,1,0]
	v_pk_fma_f32 v[4:5], v[58:59], v[58:59], v[4:5] op_sel_hi:[1,1,0]
	v_mov_b32_e32 v3, v6
	v_mov_b32_e32 v5, v7
	v_pk_add_f32 v[2:3], v[2:3], v[4:5]
	s_nop 0
	v_pk_add_f32 v[0:1], v[0:1], v[2:3]
	v_add_u32_e32 v3, -1, v28
	v_add_f32_e32 v0, v0, v1
	v_fma_f32 v4, -v3, v28, v23
	v_cmp_ge_f32_e64 s[4:5], 0, v4
	v_add_u32_e32 v4, 1, v28
	v_fma_f32 v5, -v4, v28, v23
	s_waitcnt lgkmcnt(0)
	s_nop 1
	v_add_f32_dpp v0, v0, v0 quad_perm:[1,0,3,2] row_mask:0xf bank_mask:0xf
	v_cndmask_b32_e64 v3, v28, v3, s[4:5]
	v_cmp_lt_f32_e64 s[4:5], 0, v5
	v_fma_f32 v2, -v13, v21, v15
	v_div_fmas_f32 v2, v2, v14, v21
	s_waitcnt lgkmcnt(0)
	s_nop 1
	v_add_f32_dpp v0, v0, v0 quad_perm:[2,3,0,1] row_mask:0xf bank_mask:0xf
	v_cndmask_b32_e64 v3, v3, v4, s[4:5]
	v_mul_f32_e32 v4, 0x37800000, v3
	v_cndmask_b32_e64 v3, v3, v4, s[0:1]
	v_cmp_class_f32_e64 s[0:1], v23, v111
	s_waitcnt lgkmcnt(0)
	s_nop 1
	v_add_f32_dpp v0, v0, v0 row_half_mirror row_mask:0xf bank_mask:0xf
	v_cndmask_b32_e64 v13, v3, v23, s[0:1]
	v_div_scale_f32 v15, s[0:1], v13, v13, 1.0
	v_rcp_f32_e32 v22, v15
	s_waitcnt lgkmcnt(0)
	s_nop 1
	v_add_f32_dpp v0, v0, v0 row_mirror row_mask:0xf bank_mask:0xf
	v_div_fixup_f32 v86, v2, v12, 1.0
	v_fma_f32 v2, -v15, v22, 1.0
	v_fmac_f32_e32 v22, v2, v22
	s_waitcnt vmcnt(3)
	v_pk_mul_f32 v[2:3], v[76:77], v[76:77]
	s_waitcnt lgkmcnt(0)
	v_mov_b32_e32 v1, v0
	s_nop 1
	v_permlane16_swap_b32_e32 v1, v0
	v_add_f32_e32 v0, v0, v1
	v_div_scale_f32 v12, vcc, 1.0, v13, 1.0
	v_mul_f32_e32 v14, v12, v22
	v_fma_f32 v21, -v15, v14, v12
	s_waitcnt lgkmcnt(0)
	v_mov_b32_e32 v1, v0
	s_nop 1
	v_permlane32_swap_b32_e32 v1, v0
	v_add_f32_e32 v0, v0, v1
	v_fmamk_f32 v0, v0, 0x3a800000, v104
	v_mul_f32_e32 v1, 0x4f800000, v0
	v_cmp_gt_f32_e64 s[0:1], s3, v0
	v_fmac_f32_e32 v14, v21, v22
	v_pk_mul_f32 v[16:17], v[16:17], v[86:87] op_sel_hi:[1,0]
	v_cndmask_b32_e64 v23, v0, v1, s[0:1]
	v_pk_mul_f32 v[0:1], v[78:79], v[78:79]
	v_sqrt_f32_e32 v28, v23
	v_pk_mov_b32 v[4:5], v[2:3], v[0:1] op_sel:[1,0]
	v_mov_b32_e32 v3, v1
	v_pk_add_f32 v[0:1], v[4:5], v[2:3]
	s_waitcnt vmcnt(2)
	v_pk_mul_f32 v[2:3], v[70:71], v[70:71]
	v_pk_mul_f32 v[4:5], v[68:69], v[68:69]
	v_pk_add_f32 v[0:1], v[0:1], v[0:1] op_sel:[0,1] op_sel_hi:[1,0]
	v_pk_mov_b32 v[6:7], v[4:5], v[2:3] op_sel:[1,0]
	v_mov_b32_e32 v5, v3
	v_pk_add_f32 v[2:3], v[6:7], v[4:5]
	s_waitcnt vmcnt(0)
	v_mul_f32_e32 v4, v72, v72
	v_mul_f32_e32 v5, v73, v73
	v_pk_add_f32 v[2:3], v[2:3], v[2:3] op_sel:[0,1] op_sel_hi:[1,0]
	v_mov_b32_e32 v1, v4
	v_mov_b32_e32 v3, v5
	v_pk_add_f32 v[0:1], v[0:1], v[2:3]
	v_mul_f32_e32 v2, v81, v81
	v_mul_f32_e32 v4, v83, v83
	v_mul_f32_e32 v6, v74, v74
	v_mul_f32_e32 v7, v75, v75
	v_pk_fma_f32 v[2:3], v[80:81], v[80:81], v[2:3] op_sel_hi:[1,1,0]
	v_pk_fma_f32 v[4:5], v[82:83], v[82:83], v[4:5] op_sel_hi:[1,1,0]
	v_mov_b32_e32 v3, v6
	v_mov_b32_e32 v5, v7
	v_pk_add_f32 v[2:3], v[2:3], v[4:5]
	v_pk_mul_f32 v[18:19], v[18:19], v[86:87] op_sel_hi:[1,0]
	v_pk_add_f32 v[0:1], v[0:1], v[2:3]
	v_add_u32_e32 v3, -1, v28
	v_add_f32_e32 v0, v0, v1
	v_fma_f32 v4, -v3, v28, v23
	v_cmp_ge_f32_e64 s[4:5], 0, v4
	v_add_u32_e32 v4, 1, v28
	v_fma_f32 v5, -v4, v28, v23
	s_waitcnt lgkmcnt(0)
	s_nop 1
	v_add_f32_dpp v0, v0, v0 quad_perm:[1,0,3,2] row_mask:0xf bank_mask:0xf
	v_cndmask_b32_e64 v3, v28, v3, s[4:5]
	v_cmp_lt_f32_e64 s[4:5], 0, v5
	v_fma_f32 v2, -v15, v14, v12
	v_div_fmas_f32 v2, v2, v22, v14
	s_waitcnt lgkmcnt(0)
	s_nop 1
	v_add_f32_dpp v0, v0, v0 quad_perm:[2,3,0,1] row_mask:0xf bank_mask:0xf
	v_cndmask_b32_e64 v3, v3, v4, s[4:5]
	v_mul_f32_e32 v4, 0x37800000, v3
	v_cndmask_b32_e64 v3, v3, v4, s[0:1]
	v_cmp_class_f32_e64 s[0:1], v23, v111
	s_waitcnt lgkmcnt(0)
	s_nop 1
	v_add_f32_dpp v0, v0, v0 row_half_mirror row_mask:0xf bank_mask:0xf
	v_cndmask_b32_e64 v3, v3, v23, s[0:1]
	v_div_scale_f32 v4, s[0:1], v3, v3, 1.0
	v_rcp_f32_e32 v5, v4
	s_waitcnt lgkmcnt(0)
	s_nop 1
	v_add_f32_dpp v0, v0, v0 row_mirror row_mask:0xf bank_mask:0xf
	v_div_fixup_f32 v90, v2, v13, 1.0
	v_fma_f32 v2, -v4, v5, 1.0
	v_fmac_f32_e32 v5, v2, v5
	v_div_scale_f32 v2, vcc, 1.0, v3, 1.0
	s_waitcnt lgkmcnt(0)
	v_mov_b32_e32 v1, v0
	s_nop 1
	v_permlane16_swap_b32_e32 v1, v0
	v_add_f32_e32 v0, v0, v1
	v_mul_f32_e32 v6, v2, v5
	v_fma_f32 v7, -v4, v6, v2
	v_fmac_f32_e32 v6, v7, v5
	v_fma_f32 v2, -v4, v6, v2
	s_waitcnt lgkmcnt(0)
	v_mov_b32_e32 v1, v0
	s_nop 1
	v_permlane32_swap_b32_e32 v1, v0
	v_add_f32_e32 v0, v0, v1
	v_fmamk_f32 v0, v0, 0x3a800000, v104
	v_mul_f32_e32 v1, 0x4f800000, v0
	v_cmp_gt_f32_e64 s[0:1], s3, v0
	v_div_fmas_f32 v2, v2, v5, v6
	v_div_fixup_f32 v92, v2, v3, 1.0
	v_cndmask_b32_e64 v0, v0, v1, s[0:1]
	v_sqrt_f32_e32 v1, v0
	v_pk_mul_f32 v[22:23], v[8:9], v[86:87] op_sel_hi:[1,0]
	v_pk_mul_f32 v[28:29], v[10:11], v[86:87] op_sel_hi:[1,0]
	v_pk_mul_f32 v[100:101], v[24:25], v[86:87] op_sel_hi:[1,0]
	v_add_u32_e32 v4, -1, v1
	v_fma_f32 v7, -v4, v1, v0
	v_cmp_ge_f32_e64 s[4:5], 0, v7
	v_add_u32_e32 v7, 1, v1
	v_pk_mul_f32 v[102:103], v[26:27], v[86:87] op_sel_hi:[1,0]
	v_cndmask_b32_e64 v4, v1, v4, s[4:5]
	v_fma_f32 v1, -v7, v1, v0
	v_cmp_lt_f32_e64 s[4:5], 0, v1
	v_add_u32_e32 v87, 0x8000, v85
	v_pk_mul_f32 v[32:33], v[32:33], v[86:87] op_sel_hi:[1,0]
	v_cndmask_b32_e64 v1, v4, v7, s[4:5]
	v_mul_f32_e32 v4, 0x37800000, v1
	v_cndmask_b32_e64 v1, v1, v4, s[0:1]
	v_cmp_class_f32_e64 s[0:1], v0, v111
	v_pk_mul_f32 v[34:35], v[34:35], v[86:87] op_sel_hi:[1,0]
	s_nop 0
	v_cndmask_b32_e64 v0, v1, v0, s[0:1]
	v_div_scale_f32 v1, s[0:1], v0, v0, 1.0
	v_rcp_f32_e32 v4, v1
	s_movk_i32 s0, 0xf000
	v_and_or_b32 v20, v85, s0, v84
	v_ashrrev_i32_e32 v21, 31, v20
	v_fma_f32 v2, -v1, v4, 1.0
	v_fmac_f32_e32 v4, v2, v4
	v_div_scale_f32 v2, vcc, 1.0, v0, 1.0
	v_mul_f32_e32 v3, v2, v4
	v_fma_f32 v5, -v1, v3, v2
	v_fmac_f32_e32 v3, v5, v4
	v_fma_f32 v1, -v1, v3, v2
	v_div_fmas_f32 v1, v1, v4, v3
	v_div_fixup_f32 v94, v1, v0, 1.0
	ds_read_b128 v[0:3], v30
	ds_read_b128 v[4:7], v30 offset:4096
	ds_read_b128 v[8:11], v30 offset:1024
	ds_read_b128 v[12:15], v30 offset:5120
	v_lshl_add_u64 v[96:97], v[20:21], 3, s[10:11]
	s_waitcnt lgkmcnt(2)
	v_pk_fma_f32 v[28:29], v[28:29], v[2:3], v[6:7]
	s_waitcnt lgkmcnt(0)
	v_pk_fma_f32 v[18:19], v[18:19], v[10:11], v[14:15]
	v_pk_fma_f32 v[16:17], v[16:17], v[8:9], v[12:13]
	v_pk_fma_f32 v[22:23], v[22:23], v[0:1], v[4:5]
	v_cvt_pk_bf16_f32 v16, v16, v17
	v_cvt_pk_bf16_f32 v17, v18, v19
	v_add_u32_e32 v18, 0x4000, v85
	v_and_or_b32 v18, v18, s0, v84
	v_ashrrev_i32_e32 v19, 31, v18
	v_cvt_pk_bf16_f32 v22, v22, v23
	v_cvt_pk_bf16_f32 v23, v28, v29
	v_lshl_add_u64 v[98:99], v[18:19], 3, s[10:11]
	global_store_dwordx2 v[96:97], v[22:23], off
	global_store_dwordx2 v[98:99], v[16:17], off
	ds_read_b128 v[16:19], v30 offset:2048
	ds_read_b128 v[20:23], v30 offset:6144
	ds_read_b128 v[24:27], v30 offset:3072
	ds_read_b128 v[28:31], v30 offset:7168
	s_waitcnt lgkmcnt(2)
	v_pk_fma_f32 v[100:101], v[100:101], v[16:17], v[20:21]
	s_waitcnt lgkmcnt(0)
	v_pk_fma_f32 v[34:35], v[34:35], v[26:27], v[30:31]
	v_pk_fma_f32 v[32:33], v[32:33], v[24:25], v[28:29]
	v_cvt_pk_bf16_f32 v112, v100, v101
	v_cvt_pk_bf16_f32 v32, v32, v33
	v_cvt_pk_bf16_f32 v33, v34, v35
	v_add_u32_e32 v34, 0xc000, v85
	v_and_or_b32 v100, v87, s0, v84
	v_and_or_b32 v34, v34, s0, v84
	v_pk_fma_f32 v[102:103], v[102:103], v[18:19], v[22:23]
	v_ashrrev_i32_e32 v101, 31, v100
	v_ashrrev_i32_e32 v35, 31, v34
	v_cvt_pk_bf16_f32 v113, v102, v103
	v_lshl_add_u64 v[100:101], v[100:101], 3, s[10:11]
	v_lshl_add_u64 v[102:103], v[34:35], 3, s[10:11]
	global_store_dwordx2 v[100:101], v[112:113], off
	global_store_dwordx2 v[102:103], v[32:33], off
	v_pk_mul_f32 v[32:33], v[52:53], v[90:91] op_sel_hi:[1,0]
	v_pk_mul_f32 v[34:35], v[54:55], v[90:91] op_sel_hi:[1,0]
	v_pk_fma_f32 v[32:33], v[32:33], v[0:1], v[4:5]
	v_pk_fma_f32 v[34:35], v[34:35], v[2:3], v[6:7]
	v_cvt_pk_bf16_f32 v32, v32, v33
	v_cvt_pk_bf16_f32 v33, v34, v35
	global_store_dwordx2 v[96:97], v[32:33], off offset:128
	v_pk_mul_f32 v[32:33], v[40:41], v[90:91] op_sel_hi:[1,0]
	v_pk_mul_f32 v[34:35], v[42:43], v[90:91] op_sel_hi:[1,0]
	v_pk_fma_f32 v[32:33], v[32:33], v[8:9], v[12:13]
	v_pk_fma_f32 v[34:35], v[34:35], v[10:11], v[14:15]
	v_cvt_pk_bf16_f32 v32, v32, v33
	v_cvt_pk_bf16_f32 v33, v34, v35
	global_store_dwordx2 v[98:99], v[32:33], off offset:128
	v_pk_mul_f32 v[32:33], v[48:49], v[90:91] op_sel_hi:[1,0]
	v_pk_mul_f32 v[34:35], v[50:51], v[90:91] op_sel_hi:[1,0]
	v_pk_fma_f32 v[32:33], v[32:33], v[16:17], v[20:21]
	v_pk_fma_f32 v[34:35], v[34:35], v[18:19], v[22:23]
	v_cvt_pk_bf16_f32 v32, v32, v33
	v_cvt_pk_bf16_f32 v33, v34, v35
	global_store_dwordx2 v[100:101], v[32:33], off offset:128
	v_pk_mul_f32 v[32:33], v[36:37], v[90:91] op_sel_hi:[1,0]
	v_pk_mul_f32 v[34:35], v[38:39], v[90:91] op_sel_hi:[1,0]
	v_pk_fma_f32 v[32:33], v[32:33], v[24:25], v[28:29]
	v_pk_fma_f32 v[34:35], v[34:35], v[26:27], v[30:31]
	v_cvt_pk_bf16_f32 v32, v32, v33
	v_cvt_pk_bf16_f32 v33, v34, v35
	global_store_dwordx2 v[102:103], v[32:33], off offset:128
	v_pk_mul_f32 v[32:33], v[64:65], v[92:93] op_sel_hi:[1,0]
	v_pk_mul_f32 v[34:35], v[66:67], v[92:93] op_sel_hi:[1,0]
	v_pk_fma_f32 v[32:33], v[0:1], v[32:33], v[4:5]
	v_pk_fma_f32 v[34:35], v[2:3], v[34:35], v[6:7]
	v_cvt_pk_bf16_f32 v32, v32, v33
	v_cvt_pk_bf16_f32 v33, v34, v35
	global_store_dwordx2 v[96:97], v[32:33], off offset:256
	v_pk_mul_f32 v[32:33], v[60:61], v[92:93] op_sel_hi:[1,0]
	v_pk_mul_f32 v[34:35], v[62:63], v[92:93] op_sel_hi:[1,0]
	v_pk_fma_f32 v[32:33], v[32:33], v[8:9], v[12:13]
	v_pk_fma_f32 v[34:35], v[34:35], v[10:11], v[14:15]
	v_cvt_pk_bf16_f32 v32, v32, v33
	v_cvt_pk_bf16_f32 v33, v34, v35
	global_store_dwordx2 v[98:99], v[32:33], off offset:256
	v_pk_mul_f32 v[32:33], v[56:57], v[92:93] op_sel_hi:[1,0]
	v_pk_mul_f32 v[34:35], v[58:59], v[92:93] op_sel_hi:[1,0]
	v_pk_fma_f32 v[32:33], v[32:33], v[16:17], v[20:21]
	v_pk_fma_f32 v[34:35], v[34:35], v[18:19], v[22:23]
	v_cvt_pk_bf16_f32 v32, v32, v33
	v_cvt_pk_bf16_f32 v33, v34, v35
	global_store_dwordx2 v[100:101], v[32:33], off offset:256
	v_pk_mul_f32 v[32:33], v[44:45], v[92:93] op_sel_hi:[1,0]
	v_pk_mul_f32 v[34:35], v[46:47], v[92:93] op_sel_hi:[1,0]
	v_pk_fma_f32 v[32:33], v[32:33], v[24:25], v[28:29]
	v_pk_fma_f32 v[34:35], v[34:35], v[26:27], v[30:31]
	v_cvt_pk_bf16_f32 v32, v32, v33
	v_cvt_pk_bf16_f32 v33, v34, v35
	global_store_dwordx2 v[102:103], v[32:33], off offset:256
	v_pk_mul_f32 v[32:33], v[76:77], v[94:95] op_sel_hi:[1,0]
	v_pk_mul_f32 v[34:35], v[78:79], v[94:95] op_sel_hi:[1,0]
	v_pk_fma_f32 v[32:33], v[0:1], v[32:33], v[4:5]
	v_pk_fma_f32 v[34:35], v[2:3], v[34:35], v[6:7]
	v_cvt_pk_bf16_f32 v32, v32, v33
	v_cvt_pk_bf16_f32 v33, v34, v35
	global_store_dwordx2 v[96:97], v[32:33], off offset:384
	v_pk_mul_f32 v[32:33], v[68:69], v[94:95] op_sel_hi:[1,0]
	v_pk_mul_f32 v[34:35], v[70:71], v[94:95] op_sel_hi:[1,0]
	v_pk_fma_f32 v[32:33], v[8:9], v[32:33], v[12:13]
	v_pk_fma_f32 v[34:35], v[10:11], v[34:35], v[14:15]
	v_cvt_pk_bf16_f32 v32, v32, v33
	v_cvt_pk_bf16_f32 v33, v34, v35
	global_store_dwordx2 v[98:99], v[32:33], off offset:384
	v_pk_mul_f32 v[32:33], v[80:81], v[94:95] op_sel_hi:[1,0]
	v_pk_mul_f32 v[34:35], v[82:83], v[94:95] op_sel_hi:[1,0]
	v_pk_fma_f32 v[32:33], v[16:17], v[32:33], v[20:21]
	v_pk_fma_f32 v[34:35], v[18:19], v[34:35], v[22:23]
	v_cvt_pk_bf16_f32 v32, v32, v33
	v_cvt_pk_bf16_f32 v33, v34, v35
	global_store_dwordx2 v[100:101], v[32:33], off offset:384
	v_pk_mul_f32 v[32:33], v[72:73], v[94:95] op_sel_hi:[1,0]
	v_pk_mul_f32 v[34:35], v[74:75], v[94:95] op_sel_hi:[1,0]
	v_pk_fma_f32 v[32:33], v[32:33], v[24:25], v[28:29]
	v_pk_fma_f32 v[34:35], v[34:35], v[26:27], v[30:31]
	v_cvt_pk_bf16_f32 v32, v32, v33
	v_cvt_pk_bf16_f32 v33, v34, v35
	global_store_dwordx2 v[102:103], v[32:33], off offset:384
	v_lshl_add_u64 v[32:33], s[8:9], 0, v[88:89]
	global_load_dwordx4 v[76:79], v[32:33], off nt
	global_load_dwordx4 v[68:71], v[32:33], off offset:1024 nt
	global_load_dwordx4 v[52:55], v[32:33], off offset:3072 nt
	global_load_dwordx4 v[60:63], v[32:33], off offset:2048 nt
	s_or_b32 s0, s6, 5
	s_ashr_i32 s1, s0, 31
	s_lshl_b64 s[0:1], s[0:1], 12
	s_add_u32 s0, s36, s0
	s_addc_u32 s1, s37, s1
	v_lshl_add_u64 v[44:45], s[0:1], 0, v[88:89]
	global_load_dwordx4 v[48:51], v[44:45], off nt
	global_load_dwordx4 v[40:43], v[44:45], off offset:1024 nt
	global_load_dwordx4 v[36:39], v[44:45], off offset:2048 nt
	global_load_dwordx4 v[32:35], v[44:45], off offset:3072 nt
	s_or_b32 s0, s6, 6
	s_ashr_i32 s1, s0, 31
	s_lshl_b64 s[0:1], s[0:1], 12
	s_add_u32 s0, s36, s0
	s_addc_u32 s1, s37, s1
	s_or_b32 s4, s6, 7
	s_ashr_i32 s5, s4, 31
	s_waitcnt vmcnt(7)
	v_pk_mul_f32 v[44:45], v[78:79], v[78:79]
	v_pk_mul_f32 v[46:47], v[76:77], v[76:77]
	s_nop 0
	v_pk_mov_b32 v[56:57], v[46:47], v[44:45] op_sel:[1,0]
	v_mov_b32_e32 v47, v45
	v_pk_add_f32 v[44:45], v[56:57], v[46:47]
	s_waitcnt vmcnt(6)
	v_pk_mul_f32 v[46:47], v[70:71], v[70:71]
	v_pk_mul_f32 v[56:57], v[68:69], v[68:69]
	v_pk_add_f32 v[44:45], v[44:45], v[44:45] op_sel:[0,1] op_sel_hi:[1,0]
	v_pk_mov_b32 v[58:59], v[56:57], v[46:47] op_sel:[1,0]
	v_mov_b32_e32 v57, v47
	v_pk_add_f32 v[46:47], v[58:59], v[56:57]
	s_waitcnt vmcnt(5)
	v_mul_f32_e32 v56, v52, v52
	v_mul_f32_e32 v57, v53, v53
	v_pk_add_f32 v[46:47], v[46:47], v[46:47] op_sel:[0,1] op_sel_hi:[1,0]
	v_mov_b32_e32 v45, v56
	v_mov_b32_e32 v47, v57
	v_pk_add_f32 v[44:45], v[44:45], v[46:47]
	s_waitcnt vmcnt(4)
	v_mul_f32_e32 v46, v61, v61
	v_mul_f32_e32 v56, v63, v63
	v_mul_f32_e32 v58, v54, v54
	v_mul_f32_e32 v59, v55, v55
	v_pk_fma_f32 v[46:47], v[60:61], v[60:61], v[46:47] op_sel_hi:[1,1,0]
	v_pk_fma_f32 v[56:57], v[62:63], v[62:63], v[56:57] op_sel_hi:[1,1,0]
	v_mov_b32_e32 v47, v58
	v_mov_b32_e32 v57, v59
	v_pk_add_f32 v[46:47], v[46:47], v[56:57]
	s_nop 0
	v_pk_add_f32 v[44:45], v[44:45], v[46:47]
	s_nop 0
	v_add_f32_e32 v44, v44, v45
	s_waitcnt lgkmcnt(0)
	s_nop 1
	v_add_f32_dpp v44, v44, v44 quad_perm:[1,0,3,2] row_mask:0xf bank_mask:0xf
	s_waitcnt lgkmcnt(0)
	s_nop 1
	v_add_f32_dpp v44, v44, v44 quad_perm:[2,3,0,1] row_mask:0xf bank_mask:0xf
	s_waitcnt lgkmcnt(0)
	s_nop 1
	v_add_f32_dpp v46, v44, v44 row_half_mirror row_mask:0xf bank_mask:0xf
	v_lshl_add_u64 v[44:45], s[0:1], 0, v[88:89]
	global_load_dwordx4 v[84:87], v[44:45], off nt
	global_load_dwordx4 v[80:83], v[44:45], off offset:1024 nt
	s_lshl_b64 s[0:1], s[4:5], 12
	s_add_u32 s0, s36, s0
	s_addc_u32 s1, s37, s1
	v_lshl_add_u64 v[92:93], s[0:1], 0, v[88:89]
	s_waitcnt lgkmcnt(0)
	s_nop 1
	v_add_f32_dpp v46, v46, v46 row_mirror row_mask:0xf bank_mask:0xf
	global_load_dwordx4 v[72:75], v[44:45], off offset:2048 nt
	global_load_dwordx4 v[64:67], v[44:45], off offset:3072 nt
	s_waitcnt lgkmcnt(0)
	v_mov_b32_e32 v47, v46
	s_nop 1
	v_permlane16_swap_b32_e32 v47, v46
	v_add_f32_e32 v90, v46, v47
	global_load_dwordx4 v[56:59], v[92:93], off nt
	global_load_dwordx4 v[44:47], v[92:93], off offset:1024 nt
	s_waitcnt lgkmcnt(0)
	v_mov_b32_e32 v91, v90
	s_nop 1
	v_permlane32_swap_b32_e32 v91, v90
	v_add_f32_e32 v88, v90, v91
	v_fmamk_f32 v88, v88, 0x3a800000, v104
	v_mul_f32_e32 v89, 0x4f800000, v88
	v_cmp_gt_f32_e32 vcc, s3, v88
	s_waitcnt vmcnt(9)
	v_pk_mul_f32 v[90:91], v[48:49], v[48:49]
	s_waitcnt vmcnt(4)
	v_pk_mul_f32 v[116:117], v[80:81], v[80:81]
	v_cndmask_b32_e32 v114, v88, v89, vcc
	v_pk_mul_f32 v[88:89], v[50:51], v[50:51]
	v_sqrt_f32_e32 v115, v114
	v_pk_mov_b32 v[94:95], v[90:91], v[88:89] op_sel:[1,0]
	v_mov_b32_e32 v91, v89
	v_pk_add_f32 v[88:89], v[94:95], v[90:91]
	v_pk_mul_f32 v[90:91], v[42:43], v[42:43]
	v_pk_mul_f32 v[94:95], v[40:41], v[40:41]
	v_pk_add_f32 v[88:89], v[88:89], v[88:89] op_sel:[0,1] op_sel_hi:[1,0]
	v_pk_mov_b32 v[112:113], v[94:95], v[90:91] op_sel:[1,0]
	v_mov_b32_e32 v95, v91
	v_pk_add_f32 v[90:91], v[112:113], v[94:95]
	v_mul_f32_e32 v94, v32, v32
	v_mul_f32_e32 v95, v33, v33
	v_pk_add_f32 v[90:91], v[90:91], v[90:91] op_sel:[0,1] op_sel_hi:[1,0]
	v_mov_b32_e32 v89, v94
	v_mov_b32_e32 v91, v95
	v_pk_add_f32 v[88:89], v[88:89], v[90:91]
	v_mul_f32_e32 v90, v37, v37
	v_mul_f32_e32 v94, v39, v39
	v_mul_f32_e32 v112, v34, v34
	v_mul_f32_e32 v113, v35, v35
	v_pk_fma_f32 v[90:91], v[36:37], v[36:37], v[90:91] op_sel_hi:[1,1,0]
	v_pk_fma_f32 v[94:95], v[38:39], v[38:39], v[94:95] op_sel_hi:[1,1,0]
	v_mov_b32_e32 v91, v112
	v_mov_b32_e32 v95, v113
	v_pk_add_f32 v[90:91], v[90:91], v[94:95]
	s_nop 0
	v_pk_add_f32 v[88:89], v[88:89], v[90:91]
	v_add_u32_e32 v90, -1, v115
	v_add_f32_e32 v88, v88, v89
	v_fma_f32 v91, -v90, v115, v114
	v_cmp_ge_f32_e64 s[0:1], 0, v91
	v_add_u32_e32 v91, 1, v115
	v_fma_f32 v94, -v91, v115, v114
	s_waitcnt lgkmcnt(0)
	s_nop 1
	v_add_f32_dpp v88, v88, v88 quad_perm:[1,0,3,2] row_mask:0xf bank_mask:0xf
	v_cndmask_b32_e64 v90, v115, v90, s[0:1]
	v_cmp_lt_f32_e64 s[0:1], 0, v94
	s_waitcnt lgkmcnt(0)
	s_nop 1
	v_add_f32_dpp v88, v88, v88 quad_perm:[2,3,0,1] row_mask:0xf bank_mask:0xf
	v_cndmask_b32_e64 v90, v90, v91, s[0:1]
	v_mul_f32_e32 v91, 0x37800000, v90
	v_cndmask_b32_e32 v90, v90, v91, vcc
	v_cmp_class_f32_e32 vcc, v114, v111
	s_waitcnt lgkmcnt(0)
	s_nop 1
	v_add_f32_dpp v94, v88, v88 row_half_mirror row_mask:0xf bank_mask:0xf
	v_cndmask_b32_e32 v120, v90, v114, vcc
	v_div_scale_f32 v121, s[0:1], v120, v120, 1.0
	v_rcp_f32_e32 v122, v121
	s_waitcnt lgkmcnt(0)
	s_nop 1
	v_add_f32_dpp v94, v94, v94 row_mirror row_mask:0xf bank_mask:0xf
	global_load_dwordx4 v[88:91], v[92:93], off offset:3072 nt
	v_fma_f32 v112, -v121, v122, 1.0
	v_fmac_f32_e32 v122, v112, v122
	v_pk_mul_f32 v[112:113], v[84:85], v[84:85]
	s_waitcnt lgkmcnt(0)
	v_mov_b32_e32 v95, v94
	s_nop 1
	v_permlane16_swap_b32_e32 v95, v94
	v_add_f32_e32 v124, v94, v95
	v_pk_mul_f32 v[94:95], v[86:87], v[86:87]
	v_pk_mov_b32 v[114:115], v[112:113], v[94:95] op_sel:[1,0]
	v_mov_b32_e32 v113, v95
	global_load_dwordx4 v[92:95], v[92:93], off offset:2048 nt
	v_pk_add_f32 v[112:113], v[114:115], v[112:113]
	v_pk_mul_f32 v[114:115], v[82:83], v[82:83]
	v_pk_add_f32 v[112:113], v[112:113], v[112:113] op_sel:[0,1] op_sel_hi:[1,0]
	v_pk_mov_b32 v[118:119], v[116:117], v[114:115] op_sel:[1,0]
	s_waitcnt lgkmcnt(0)
	v_mov_b32_e32 v125, v124
	s_nop 1
	v_permlane32_swap_b32_e32 v125, v124
	v_add_f32_e32 v114, v124, v125
	v_fmamk_f32 v114, v114, 0x3a800000, v104
	v_mov_b32_e32 v117, v115
	v_mul_f32_e32 v115, 0x4f800000, v114
	v_cmp_gt_f32_e64 s[0:1], s3, v114
	v_div_scale_f32 v123, vcc, 1.0, v120, 1.0
	s_nop 0
	v_cndmask_b32_e64 v124, v114, v115, s[0:1]
	v_pk_add_f32 v[114:115], v[118:119], v[116:117]
	s_waitcnt vmcnt(4)
	v_mul_f32_e32 v116, v64, v64
	v_mul_f32_e32 v117, v65, v65
	v_pk_add_f32 v[114:115], v[114:115], v[114:115] op_sel:[0,1] op_sel_hi:[1,0]
	v_mov_b32_e32 v113, v116
	v_mov_b32_e32 v115, v117
	v_pk_add_f32 v[112:113], v[112:113], v[114:115]
	v_mul_f32_e32 v114, v73, v73
	v_mul_f32_e32 v116, v75, v75
	v_mul_f32_e32 v118, v66, v66
	v_mul_f32_e32 v119, v67, v67
	v_pk_fma_f32 v[114:115], v[72:73], v[72:73], v[114:115] op_sel_hi:[1,1,0]
	v_pk_fma_f32 v[116:117], v[74:75], v[74:75], v[116:117] op_sel_hi:[1,1,0]
	v_mov_b32_e32 v115, v118
	v_mov_b32_e32 v117, v119
	v_pk_add_f32 v[114:115], v[114:115], v[116:117]
	v_sqrt_f32_e32 v118, v124
	v_pk_add_f32 v[112:113], v[112:113], v[114:115]
	v_mul_f32_e32 v126, v123, v122
	v_add_f32_e32 v112, v112, v113
	v_add_u32_e32 v115, -1, v118
	v_fma_f32 v116, -v115, v118, v124
	v_cmp_ge_f32_e64 s[4:5], 0, v116
	v_add_u32_e32 v116, 1, v118
	s_waitcnt lgkmcnt(0)
	s_nop 1
	v_add_f32_dpp v112, v112, v112 quad_perm:[1,0,3,2] row_mask:0xf bank_mask:0xf
	v_fma_f32 v117, -v116, v118, v124
	v_cndmask_b32_e64 v115, v118, v115, s[4:5]
	v_cmp_lt_f32_e64 s[4:5], 0, v117
	v_fma_f32 v127, -v121, v126, v123
	s_waitcnt lgkmcnt(0)
	s_nop 1
	v_add_f32_dpp v112, v112, v112 quad_perm:[2,3,0,1] row_mask:0xf bank_mask:0xf
	v_cndmask_b32_e64 v115, v115, v116, s[4:5]
	v_mul_f32_e32 v116, 0x37800000, v115
	v_fmac_f32_e32 v126, v127, v122
	v_cndmask_b32_e64 v115, v115, v116, s[0:1]
	s_waitcnt lgkmcnt(0)
	s_nop 1
	v_add_f32_dpp v112, v112, v112 row_half_mirror row_mask:0xf bank_mask:0xf
	v_cmp_class_f32_e64 s[0:1], v124, v111
	v_fma_f32 v114, -v121, v126, v123
	v_div_fmas_f32 v122, v114, v122, v126
	v_cndmask_b32_e64 v121, v115, v124, s[0:1]
	v_div_scale_f32 v123, s[0:1], v121, v121, 1.0
	s_waitcnt lgkmcnt(0)
	s_nop 1
	v_add_f32_dpp v112, v112, v112 row_mirror row_mask:0xf bank_mask:0xf
	v_rcp_f32_e32 v124, v123
	v_fma_f32 v114, -v123, v124, 1.0
	v_fmac_f32_e32 v124, v114, v124
	s_waitcnt lgkmcnt(0)
	v_mov_b32_e32 v113, v112
	s_nop 1
	v_permlane16_swap_b32_e32 v113, v112
	v_add_f32_e32 v125, v112, v113
	s_waitcnt vmcnt(3)
	v_pk_mul_f32 v[112:113], v[58:59], v[58:59]
	v_pk_mul_f32 v[114:115], v[56:57], v[56:57]
	s_nop 0
	v_pk_mov_b32 v[116:117], v[114:115], v[112:113] op_sel:[1,0]
	v_mov_b32_e32 v115, v113
	v_pk_add_f32 v[112:113], v[116:117], v[114:115]
	s_waitcnt vmcnt(2)
	v_pk_mul_f32 v[114:115], v[46:47], v[46:47]
	v_pk_mul_f32 v[116:117], v[44:45], v[44:45]
	v_pk_add_f32 v[112:113], v[112:113], v[112:113] op_sel:[0,1] op_sel_hi:[1,0]
	v_pk_mov_b32 v[118:119], v[116:117], v[114:115] op_sel:[1,0]
	v_mov_b32_e32 v117, v115
	v_pk_add_f32 v[114:115], v[118:119], v[116:117]
	s_waitcnt vmcnt(1)
	v_mul_f32_e32 v116, v88, v88
	v_mul_f32_e32 v117, v89, v89
	v_pk_add_f32 v[114:115], v[114:115], v[114:115] op_sel:[0,1] op_sel_hi:[1,0]
	v_mov_b32_e32 v113, v116
	v_mov_b32_e32 v115, v117
	v_pk_add_f32 v[112:113], v[112:113], v[114:115]
	s_waitcnt vmcnt(0)
	v_mul_f32_e32 v114, v93, v93
	v_mul_f32_e32 v116, v90, v90
	v_pk_fma_f32 v[114:115], v[92:93], v[92:93], v[114:115] op_sel_hi:[1,1,0]
	v_div_fixup_f32 v118, v122, v120, 1.0
	v_mov_b32_e32 v115, v116
	v_mul_f32_e32 v116, v95, v95
	v_pk_fma_f32 v[116:117], v[94:95], v[94:95], v[116:117] op_sel_hi:[1,1,0]
	s_nop 0
	v_mul_f32_e32 v117, v91, v91
	v_pk_add_f32 v[114:115], v[114:115], v[116:117]
	v_pk_add_f32 v[112:113], v[112:113], v[114:115]
	v_div_scale_f32 v117, vcc, 1.0, v121, 1.0
	v_add_f32_e32 v112, v112, v113
	s_waitcnt lgkmcnt(1)
	v_mov_b32_e32 v116, v125
	s_nop 1
	v_permlane32_swap_b32_e32 v116, v125
	v_add_f32_e32 v116, v125, v116
	v_fmamk_f32 v116, v116, 0x3a800000, v104
	v_mul_f32_e32 v119, 0x4f800000, v116
	v_cmp_gt_f32_e64 s[0:1], s3, v116
	s_waitcnt lgkmcnt(0)
	s_nop 1
	v_add_f32_dpp v110, v112, v112 quad_perm:[1,0,3,2] row_mask:0xf bank_mask:0xf
	v_cndmask_b32_e64 v116, v116, v119, s[0:1]
	v_sqrt_f32_e32 v119, v116
	v_mul_f32_e32 v114, v117, v124
	v_fma_f32 v115, -v123, v114, v117
	s_waitcnt lgkmcnt(0)
	s_nop 1
	v_add_f32_dpp v109, v110, v110 quad_perm:[2,3,0,1] row_mask:0xf bank_mask:0xf
	v_fmac_f32_e32 v114, v115, v124
	v_add_u32_e32 v115, -1, v119
	v_fma_f32 v113, -v123, v114, v117
	v_fma_f32 v117, -v115, v119, v116
	s_waitcnt lgkmcnt(0)
	s_nop 1
	v_add_f32_dpp v108, v109, v109 row_half_mirror row_mask:0xf bank_mask:0xf
	v_cmp_ge_f32_e64 s[4:5], 0, v117
	v_pk_mul_f32 v[76:77], v[76:77], v[118:119] op_sel_hi:[1,0]
	v_pk_mul_f32 v[78:79], v[78:79], v[118:119] op_sel_hi:[1,0]
	v_cndmask_b32_e64 v112, v119, v115, s[4:5]
	s_waitcnt lgkmcnt(0)
	s_nop 1
	v_add_f32_dpp v107, v108, v108 row_mirror row_mask:0xf bank_mask:0xf
	v_add_u32_e32 v115, 1, v119
	v_fma_f32 v117, -v115, v119, v116
	v_cmp_lt_f32_e64 s[4:5], 0, v117
	v_div_fmas_f32 v106, v113, v124, v114
	s_waitcnt lgkmcnt(0)
	v_mov_b32_e32 v108, v107
	s_nop 1
	v_permlane16_swap_b32_e32 v108, v107
	v_add_f32_e32 v107, v107, v108
	v_cndmask_b32_e64 v110, v112, v115, s[4:5]
	v_mul_f32_e32 v112, 0x37800000, v110
	v_cndmask_b32_e64 v110, v110, v112, s[0:1]
	v_cmp_class_f32_e64 s[0:1], v116, v111
	v_div_fixup_f32 v106, v106, v121, 1.0
	v_pk_mul_f32 v[68:69], v[68:69], v[118:119] op_sel_hi:[1,0]
	v_cndmask_b32_e64 v109, v110, v116, s[0:1]
	v_div_scale_f32 v110, s[0:1], v109, v109, 1.0
	v_rcp_f32_e32 v112, v110
	s_waitcnt lgkmcnt(0)
	v_mov_b32_e32 v105, v107
	s_nop 1
	v_permlane32_swap_b32_e32 v105, v107
	v_add_f32_e32 v105, v107, v105
	v_fmac_f32_e32 v104, 0x3a800000, v105
	v_mul_f32_e32 v105, 0x4f800000, v104
	v_cmp_gt_f32_e64 s[0:1], s3, v104
	v_fma_f32 v113, -v110, v112, 1.0
	v_fmac_f32_e32 v112, v113, v112
	v_cndmask_b32_e64 v104, v104, v105, s[0:1]
	v_div_scale_f32 v108, vcc, 1.0, v109, 1.0
	v_sqrt_f32_e32 v105, v104
	v_mul_f32_e32 v113, v108, v112
	v_fma_f32 v107, -v110, v113, v108
	v_fmac_f32_e32 v113, v107, v112
	v_fma_f32 v107, -v110, v113, v108
	v_add_u32_e32 v108, -1, v105
	v_fma_f32 v110, -v108, v105, v104
	v_cmp_ge_f32_e64 s[4:5], 0, v110
	v_add_u32_e32 v110, 1, v105
	v_pk_mul_f32 v[70:71], v[70:71], v[118:119] op_sel_hi:[1,0]
	v_cndmask_b32_e64 v108, v105, v108, s[4:5]
	v_fma_f32 v105, -v110, v105, v104
	v_cmp_lt_f32_e64 s[4:5], 0, v105
	v_pk_mul_f32 v[60:61], v[60:61], v[118:119] op_sel_hi:[1,0]
	v_pk_mul_f32 v[62:63], v[62:63], v[118:119] op_sel_hi:[1,0]
	v_cndmask_b32_e64 v105, v108, v110, s[4:5]
	v_mul_f32_e32 v108, 0x37800000, v105
	v_cndmask_b32_e64 v105, v105, v108, s[0:1]
	v_cmp_class_f32_e64 s[0:1], v104, v111
	v_pk_mul_f32 v[52:53], v[52:53], v[118:119] op_sel_hi:[1,0]
	v_pk_mul_f32 v[54:55], v[54:55], v[118:119] op_sel_hi:[1,0]
	v_cndmask_b32_e64 v105, v105, v104, s[0:1]
	v_div_scale_f32 v108, s[0:1], v105, v105, 1.0
	v_rcp_f32_e32 v110, v108
	v_div_fmas_f32 v104, v107, v112, v113
	v_div_fixup_f32 v104, v104, v109, 1.0
	v_pk_fma_f32 v[78:79], v[2:3], v[78:79], v[6:7]
	v_fma_f32 v107, -v108, v110, 1.0
	v_fmac_f32_e32 v110, v107, v110
	v_div_scale_f32 v107, vcc, 1.0, v105, 1.0
	v_mul_f32_e32 v109, v107, v110
	v_fma_f32 v111, -v108, v109, v107
	v_fmac_f32_e32 v109, v111, v110
	v_fma_f32 v107, -v108, v109, v107
	v_div_fmas_f32 v107, v107, v110, v109
	v_pk_mul_f32 v[48:49], v[48:49], v[106:107] op_sel_hi:[1,0]
	v_pk_mul_f32 v[50:51], v[50:51], v[106:107] op_sel_hi:[1,0]
	v_pk_mul_f32 v[40:41], v[40:41], v[106:107] op_sel_hi:[1,0]
	v_pk_mul_f32 v[42:43], v[42:43], v[106:107] op_sel_hi:[1,0]
	v_pk_mul_f32 v[36:37], v[36:37], v[106:107] op_sel_hi:[1,0]
	v_pk_mul_f32 v[38:39], v[38:39], v[106:107] op_sel_hi:[1,0]
	v_pk_mul_f32 v[32:33], v[32:33], v[106:107] op_sel_hi:[1,0]
	v_pk_mul_f32 v[34:35], v[34:35], v[106:107] op_sel_hi:[1,0]
	v_pk_fma_f32 v[76:77], v[0:1], v[76:77], v[4:5]
	v_pk_fma_f32 v[70:71], v[10:11], v[70:71], v[14:15]
	v_pk_fma_f32 v[68:69], v[8:9], v[68:69], v[12:13]
	v_pk_fma_f32 v[62:63], v[18:19], v[62:63], v[22:23]
	v_pk_fma_f32 v[60:61], v[16:17], v[60:61], v[20:21]
	v_pk_fma_f32 v[54:55], v[26:27], v[54:55], v[30:31]
	v_pk_fma_f32 v[52:53], v[24:25], v[52:53], v[28:29]
	v_pk_fma_f32 v[50:51], v[2:3], v[50:51], v[6:7]
	v_pk_fma_f32 v[48:49], v[0:1], v[48:49], v[4:5]
	v_pk_fma_f32 v[42:43], v[10:11], v[42:43], v[14:15]
	v_pk_fma_f32 v[40:41], v[8:9], v[40:41], v[12:13]
	v_pk_fma_f32 v[38:39], v[18:19], v[38:39], v[22:23]
	v_pk_fma_f32 v[36:37], v[16:17], v[36:37], v[20:21]
	v_pk_fma_f32 v[34:35], v[26:27], v[34:35], v[30:31]
	v_pk_fma_f32 v[32:33], v[24:25], v[32:33], v[28:29]
	v_cvt_pk_bf16_f32 v76, v76, v77
	v_cvt_pk_bf16_f32 v77, v78, v79
	v_cvt_pk_bf16_f32 v68, v68, v69
	v_cvt_pk_bf16_f32 v69, v70, v71
	v_cvt_pk_bf16_f32 v60, v60, v61
	v_cvt_pk_bf16_f32 v61, v62, v63
	v_cvt_pk_bf16_f32 v52, v52, v53
	v_cvt_pk_bf16_f32 v53, v54, v55
	v_cvt_pk_bf16_f32 v48, v48, v49
	v_cvt_pk_bf16_f32 v49, v50, v51
	v_cvt_pk_bf16_f32 v40, v40, v41
	v_cvt_pk_bf16_f32 v41, v42, v43
	v_cvt_pk_bf16_f32 v36, v36, v37
	v_cvt_pk_bf16_f32 v37, v38, v39
	v_cvt_pk_bf16_f32 v32, v32, v33
	v_cvt_pk_bf16_f32 v33, v34, v35
	global_store_dwordx2 v[96:97], v[76:77], off offset:512
	global_store_dwordx2 v[98:99], v[68:69], off offset:512
	global_store_dwordx2 v[100:101], v[60:61], off offset:512
	global_store_dwordx2 v[102:103], v[52:53], off offset:512
	global_store_dwordx2 v[96:97], v[48:49], off offset:640
	global_store_dwordx2 v[98:99], v[40:41], off offset:640
	global_store_dwordx2 v[100:101], v[36:37], off offset:640
	global_store_dwordx2 v[102:103], v[32:33], off offset:640
	v_pk_mul_f32 v[32:33], v[84:85], v[104:105] op_sel_hi:[1,0]
	v_pk_mul_f32 v[34:35], v[86:87], v[104:105] op_sel_hi:[1,0]
	v_pk_fma_f32 v[32:33], v[0:1], v[32:33], v[4:5]
	v_pk_fma_f32 v[34:35], v[2:3], v[34:35], v[6:7]
	v_cvt_pk_bf16_f32 v32, v32, v33
	v_cvt_pk_bf16_f32 v33, v34, v35
	global_store_dwordx2 v[96:97], v[32:33], off offset:768
	v_pk_mul_f32 v[32:33], v[80:81], v[104:105] op_sel_hi:[1,0]
	v_pk_mul_f32 v[34:35], v[82:83], v[104:105] op_sel_hi:[1,0]
	v_pk_fma_f32 v[32:33], v[8:9], v[32:33], v[12:13]
	v_pk_fma_f32 v[34:35], v[10:11], v[34:35], v[14:15]
	v_cvt_pk_bf16_f32 v32, v32, v33
	v_cvt_pk_bf16_f32 v33, v34, v35
	global_store_dwordx2 v[98:99], v[32:33], off offset:768
	v_pk_mul_f32 v[32:33], v[72:73], v[104:105] op_sel_hi:[1,0]
	v_pk_mul_f32 v[34:35], v[74:75], v[104:105] op_sel_hi:[1,0]
	v_pk_fma_f32 v[32:33], v[16:17], v[32:33], v[20:21]
	v_pk_fma_f32 v[34:35], v[18:19], v[34:35], v[22:23]
	v_cvt_pk_bf16_f32 v32, v32, v33
	v_cvt_pk_bf16_f32 v33, v34, v35
	global_store_dwordx2 v[100:101], v[32:33], off offset:768
	v_pk_mul_f32 v[32:33], v[64:65], v[104:105] op_sel_hi:[1,0]
	v_pk_mul_f32 v[34:35], v[66:67], v[104:105] op_sel_hi:[1,0]
	v_pk_fma_f32 v[32:33], v[24:25], v[32:33], v[28:29]
	v_pk_fma_f32 v[34:35], v[26:27], v[34:35], v[30:31]
	v_div_fixup_f32 v108, v107, v105, 1.0
	v_cvt_pk_bf16_f32 v32, v32, v33
	v_cvt_pk_bf16_f32 v33, v34, v35
	global_store_dwordx2 v[102:103], v[32:33], off offset:768
	v_pk_mul_f32 v[32:33], v[56:57], v[108:109] op_sel_hi:[1,0]
	v_pk_mul_f32 v[34:35], v[58:59], v[108:109] op_sel_hi:[1,0]
	v_pk_fma_f32 v[0:1], v[0:1], v[32:33], v[4:5]
	v_pk_fma_f32 v[2:3], v[2:3], v[34:35], v[6:7]
	v_cvt_pk_bf16_f32 v0, v0, v1
	v_cvt_pk_bf16_f32 v1, v2, v3
	global_store_dwordx2 v[96:97], v[0:1], off offset:896
	v_pk_mul_f32 v[0:1], v[44:45], v[108:109] op_sel_hi:[1,0]
	v_pk_mul_f32 v[2:3], v[46:47], v[108:109] op_sel_hi:[1,0]
	v_pk_fma_f32 v[0:1], v[8:9], v[0:1], v[12:13]
	v_pk_fma_f32 v[2:3], v[10:11], v[2:3], v[14:15]
	v_cvt_pk_bf16_f32 v0, v0, v1
	v_cvt_pk_bf16_f32 v1, v2, v3
	global_store_dwordx2 v[98:99], v[0:1], off offset:896
	v_pk_mul_f32 v[0:1], v[92:93], v[108:109] op_sel_hi:[1,0]
	v_pk_mul_f32 v[2:3], v[94:95], v[108:109] op_sel_hi:[1,0]
	v_pk_fma_f32 v[0:1], v[16:17], v[0:1], v[20:21]
	v_pk_fma_f32 v[2:3], v[18:19], v[2:3], v[22:23]
	v_cvt_pk_bf16_f32 v0, v0, v1
	v_cvt_pk_bf16_f32 v1, v2, v3
	global_store_dwordx2 v[100:101], v[0:1], off offset:896
	v_pk_mul_f32 v[0:1], v[88:89], v[108:109] op_sel_hi:[1,0]
	v_pk_mul_f32 v[2:3], v[90:91], v[108:109] op_sel_hi:[1,0]
	v_pk_fma_f32 v[0:1], v[24:25], v[0:1], v[28:29]
	v_pk_fma_f32 v[2:3], v[26:27], v[2:3], v[30:31]
	v_cvt_pk_bf16_f32 v0, v0, v1
	v_cvt_pk_bf16_f32 v1, v2, v3
	global_store_dwordx2 v[102:103], v[0:1], off offset:896
